# merge epilogue de-serialised in both code instances (scan-WG and helper): loads issued before the write-through stores
# baseline (speedup 1.0000x reference)
.LBB0_537:
	s_or_b64 exec, exec, s[0:1]
	s_and_b64 s[0:1], s[36:37], exec
	s_cselect_b32 s28, 16, 0x1000
	s_add_u32 s64, s76, 0x13d00000
	s_addc_u32 s65, s77, 0
	s_bfe_u32 s68, s96, 0x20006
	s_mul_i32 s0, s68, 0x3700
	s_add_i32 s71, s0, 0
	s_and_b32 s0, s96, 0xffffff00
	s_lshr_b32 s74, s96, 8
	s_add_i32 s84, s0, 0
	s_lshl_b32 s11, s74, 5
	s_add_i32 s80, s84, 0x12600
	s_cmpk_lt_u32 s96, 0x540
	v_readlane_b32 s20, v255, 31
	s_cselect_b64 s[40:41], -1, 0
	s_add_i32 s12, s20, -4
	s_lshl_b32 s13, s12, 2
	s_lshl_b32 s22, s12, 10
	s_cmpk_lt_u32 s96, 0x440
	s_cselect_b64 s[42:43], -1, 0
	s_lshl_b32 s66, s20, 10
	s_cmpk_lt_u32 s96, 0x340
	s_cselect_b64 s[46:47], -1, 0
	s_add_i32 s14, s20, 4
	s_lshl_b32 s15, s14, 2
	s_lshl_b32 s23, s14, 10
	s_cmpk_lt_u32 s96, 0x240
	s_cselect_b64 s[48:49], -1, 0
	s_add_i32 s16, s20, 8
	s_lshl_b32 s17, s16, 2
	s_lshl_b32 s24, s16, 10
	s_cmp_eq_u32 s20, 4
	s_cselect_b64 s[50:51], -1, 0
	s_cmp_eq_u32 s20, 2
	s_mov_b32 s0, 0xfc00000
	s_cselect_b32 s38, s0, 0x13d00000
	s_add_u32 s8, s76, s6
	s_addc_u32 s9, s77, 0
	s_mul_i32 s0, s20, 0x2400
	s_add_i32 s1, 0, 0x1a900
	s_add_i32 s81, s1, s0
	s_lshl_b32 s0, s74, 7
	s_add_i32 s83, s0, 0
	s_add_i32 s82, s81, 0x2000
	s_add_i32 s83, s83, 0x14800
	s_add_i32 s84, s84, 0x12400
	s_lshl_b32 s29, s20, 5
	s_add_u32 s6, s64, s6
	s_addc_u32 s7, s65, 0
	s_lshl_b32 s85, s33, 10
	s_add_u32 s18, s76, 0x10000
	v_writelane_b32 v255, s96, 33
	s_addc_u32 s19, s77, 0
	v_lshl_or_b32 v11, s68, 4, v9
	v_writelane_b32 v255, s18, 34
	v_add_u32_e32 v25, 1, v11
	v_lshlrev_b32_e32 v27, 3, v38
	v_writelane_b32 v255, s19, 35
	v_lshlrev_b32_e32 v10, 7, v25
	v_and_b32_e32 v22, 8, v27
	s_add_i32 s0, 0, 0x1cd00
	s_add_i32 s18, 0, 0x1f100
	v_add3_u32 v91, s1, v10, v22
	v_add3_u32 v92, s0, v10, v22
	v_add3_u32 v93, s18, v10, v22
	v_lshlrev_b32_e32 v10, 8, v25
	s_add_i32 s19, 0, 0x23900
	v_add3_u32 v28, s19, v10, v22
	v_lshlrev_b32_e32 v10, 7, v11
	v_add3_u32 v94, s1, v10, v22
	v_add3_u32 v95, s0, v10, v22
	v_add3_u32 v96, s18, v10, v22
	v_lshlrev_b32_e32 v10, 8, v11
	v_add3_u32 v29, s19, v10, v22
	v_add_u32_e32 v10, 1, v89
	s_add_i32 s19, 0, 0x21500
	v_lshl_add_u32 v32, v10, 7, s19
	v_xor_b32_e32 v10, v10, v39
	v_lshlrev_b32_e32 v10, 4, v10
	v_and_b32_e32 v33, 0x70, v10
	v_lshlrev_b32_e32 v10, 7, v89
	v_add_u32_e32 v34, s19, v10
	s_add_i32 s19, 0, 0x12800
	s_cmp_lg_u32 s12, 16
	v_add_u32_e32 v36, s19, v10
	v_or_b32_e32 v10, s13, v38
	s_cselect_b64 vcc, -1, 0
	v_xor_b32_e32 v22, v89, v39
	v_cndmask_b32_e32 v98, 64, v10, vcc
	v_bitop3_b32 v10, v38, v39, s13 bitop3:0x36
	v_lshlrev_b32_e32 v22, 4, v22
	v_and_or_b32 v10, v10, 7, v41
	v_and_b32_e32 v35, 0x70, v22
	v_lshlrev_b32_e32 v22, 4, v10
	v_mov_b32_e32 v10, 0
	v_mov_b32_e32 v23, v10
	s_cmp_lg_u32 s20, 16
	v_lshl_add_u64 v[48:49], s[4:5], 0, v[22:23]
	v_or_b32_e32 v22, s3, v38
	s_cselect_b64 vcc, -1, 0
	v_cndmask_b32_e32 v99, 64, v22, vcc
	v_bitop3_b32 v22, v38, v39, s3 bitop3:0x36
	v_and_or_b32 v22, v22, 7, v41
	v_lshlrev_b32_e32 v22, 4, v22
	s_cmp_lg_u32 s14, 16
	v_lshl_add_u64 v[50:51], s[4:5], 0, v[22:23]
	v_or_b32_e32 v22, s15, v38
	s_cselect_b64 vcc, -1, 0
	v_cndmask_b32_e32 v100, 64, v22, vcc
	v_bitop3_b32 v22, v38, v39, s15 bitop3:0x36
	v_and_or_b32 v22, v22, 7, v41
	v_lshlrev_b32_e32 v22, 4, v22
	s_cmp_lg_u32 s16, 16
	v_lshl_add_u64 v[52:53], s[4:5], 0, v[22:23]
	v_or_b32_e32 v22, s17, v38
	s_cselect_b64 vcc, -1, 0
	v_cndmask_b32_e32 v101, 64, v22, vcc
	v_bitop3_b32 v22, v38, v39, s17 bitop3:0x36
	v_and_or_b32 v22, v22, 7, v41
	v_lshlrev_b32_e32 v22, 4, v22
	v_lshl_add_u64 v[54:55], s[4:5], 0, v[22:23]
	v_xor_b32_e32 v22, v38, v20
	s_movk_i32 s10, 0x3700
	v_or_b32_e32 v22, v22, v41
	v_lshlrev_b32_e32 v41, 5, v9
	v_lshrrev_b32_e32 v45, 7, v42
	v_cmp_gt_u32_e64 s[0:1], 16, v40
	v_or_b32_e32 v103, v27, v41
	v_lshl_add_u32 v104, v40, 2, s71
	v_add_u32_e32 v40, s71, v41
	v_lshrrev_b32_e32 v41, 2, v9
	v_mul_lo_u32 v45, v45, s10
	v_or_b32_e32 v41, v90, v41
	v_add_u32_e32 v67, 0, v45
	v_bfe_u32 v45, v42, 3, 4
	v_mul_u32_u24_e32 v41, 0x48, v41
	v_and_b32_e32 v21, 12, v21
	v_mul_u32_u24_e32 v45, 0x48, v45
	v_or_b32_e32 v24, s11, v90
	v_add_lshl_u32 v105, v21, v41, 1
	v_lshl_or_b32 v21, v89, 6, v8
	v_add_lshl_u32 v8, v45, v8, 1
	v_mov_b32_e32 v45, v10
	v_and_b32_e32 v26, 7, v25
	v_lshl_add_u64 v[60:61], s[6:7], 0, v[44:45]
	v_cmp_eq_u32_e64 s[6:7], 0, v42
	v_lshrrev_b32_e32 v42, 3, v24
	v_and_b32_e32 v62, 8, v42
	v_bitop3_b32 v63, v42, v26, 5 bitop3:0x6c
	v_or_b32_e32 v63, v63, v62
	v_lshlrev_b32_e32 v68, 4, v63
	v_add_u32_e32 v63, 64, v24
	v_bitop3_b32 v45, v42, v25, 7 bitop3:0x78
	v_lshrrev_b32_e32 v64, 3, v63
	v_xor_b32_e32 v69, v42, v20
	v_bitop3_b32 v42, v42, v20, 5 bitop3:0x6c
	v_and_b32_e32 v65, 8, v64
	v_or_b32_e32 v42, v42, v62
	v_bitop3_b32 v62, v64, v20, 5 bitop3:0x6c
	v_or_b32_e32 v62, v62, v65
	v_lshlrev_b32_e32 v108, 4, v69
	v_lshlrev_b32_e32 v69, 4, v62
	v_or_b32_e32 v62, 16, v24
	v_lshlrev_b32_e32 v22, 4, v22
	v_lshlrev_b32_e32 v71, 1, v63
	v_lshrrev_b32_e32 v63, 3, v62
	v_lshl_add_u64 v[56:57], s[4:5], 0, v[22:23]
	v_xor_b32_e32 v22, v88, v20
	v_bitop3_b32 v26, v64, v26, 5 bitop3:0x6c
	v_bitop3_b32 v64, v63, v25, 7 bitop3:0x78
	v_lshlrev_b32_e32 v22, 4, v22
	v_or_b32_e32 v26, v26, v65
	v_lshlrev_b32_e32 v111, 4, v64
	v_and_b32_e32 v64, 8, v63
	v_bitop3_b32 v65, v63, v25, 7 bitop3:0x28
	s_movk_i32 s18, 0x48
	v_lshl_add_u64 v[58:59], s[8:9], 0, v[22:23]
	v_or_b32_e32 v23, s11, v9
	v_or_b32_e32 v65, v65, v64
	v_mul_u32_u24_e32 v30, 0x48, v11
	v_mul_u32_u24_e32 v31, 0x48, v9
	v_lshlrev_b32_e32 v97, 2, v11
	v_or_b32_e32 v22, 16, v90
	v_lshlrev_b32_e32 v72, 4, v65
	v_add_u32_e32 v65, 0x50, v24
	v_mul_lo_u32 v23, v23, s18
	v_mad_u32_u24 v11, v11, s18, 32
	v_lshlrev_b32_e32 v70, 1, v24
	v_add_lshl_u32 v109, v24, v30, 1
	v_add_lshl_u32 v110, v24, v31, 1
	v_lshrrev_b32_e32 v73, 3, v65
	v_xor_b32_e32 v75, v63, v20
	v_bitop3_b32 v63, v63, v20, 7 bitop3:0x6c
	v_add_lshl_u32 v113, v62, v30, 1
	v_add_lshl_u32 v115, v30, v90, 1
	v_add_lshl_u32 v116, v22, v30, 1
	v_add_u32_e32 v30, 0x480, v23
	v_add_lshl_u32 v119, v11, v90, 1
	v_add_lshl_u32 v120, v11, v22, 1
	v_or_b32_e32 v11, 32, v90
	v_lshlrev_b32_e32 v123, 2, v24
	v_or_b32_e32 v24, 1, v90
	v_cmp_eq_u32_e32 vcc, v90, v9
	v_lshlrev_b32_e32 v106, 5, v20
	v_and_b32_e32 v74, 8, v73
	v_bitop3_b32 v25, v73, v25, 7 bitop3:0x28
	v_or_b32_e32 v63, v63, v64
	v_bitop3_b32 v20, v73, v20, 7 bitop3:0x6c
	v_lshlrev_b32_e32 v73, 1, v62
	v_add_lshl_u32 v114, v62, v31, 1
	v_add_lshl_u32 v118, v30, v90, 1
	v_add_lshl_u32 v122, v11, v30, 1
	v_lshlrev_b32_e32 v124, 2, v62
	v_or_b32_e32 v30, 2, v90
	v_cndmask_b32_e64 v62, 0, 1.0, vcc
	v_cmp_eq_u32_e32 vcc, v24, v9
	v_lshlrev_b32_e32 v112, 4, v75
	v_lshlrev_b32_e32 v75, 4, v63
	v_add_lshl_u32 v117, v90, v23, 1
	v_add_lshl_u32 v121, v11, v23, 1
	v_add_lshl_u32 v125, v90, v31, 1
	v_add_lshl_u32 v23, v11, v31, 1
	v_or_b32_e32 v31, 3, v90
	v_cndmask_b32_e64 v63, 0, 1.0, vcc
	v_cmp_eq_u32_e32 vcc, v30, v9
	v_cmp_eq_u32_e64 s[4:5], 0, v9
	v_mad_u32_u24 v37, v9, s18, 16
	v_cmp_lt_u32_e64 s[8:9], v90, v9
	v_cmp_gt_u32_e64 s[10:11], v90, v9
	v_cmp_lt_u32_e64 s[12:13], v24, v9
	v_cmp_lt_u32_e64 s[14:15], v30, v9
	v_cmp_gt_u32_e64 s[16:17], v30, v9
	v_cmp_lt_u32_e64 s[18:19], v31, v9
	v_cmp_gt_u32_e64 s[20:21], v31, v9
	v_cndmask_b32_e64 v64, 0, 1.0, vcc
	v_cmp_eq_u32_e32 vcc, v31, v9
	v_lshlrev_b32_e32 v9, 2, v9
	v_lshl_add_u32 v24, v38, 10, s97
	s_mov_b32 s3, 0xdc00
	v_add3_u32 v126, v24, v9, s3
	v_and_b32_e32 v9, 3, v39
	s_movk_i32 s25, 0x2400
	v_lshlrev_b32_e32 v43, 2, v21
	v_lshlrev_b32_e32 v21, 1, v21
	v_lshl_or_b32 v9, v9, 3, s29
	v_lshlrev_b32_e32 v24, 1, v41
	s_waitcnt lgkmcnt(0)
	s_barrier
	v_lshlrev_b32_e32 v66, 2, v89
	v_or_b32_e32 v25, v25, v74
	v_or_b32_e32 v20, v20, v74
	v_add3_u32 v128, v9, v24, s25
	v_mov_b32_e32 v9, 0x3540
	v_add_u32_e32 v151, v67, v8
	v_add_u32_e32 v8, 0, v21
	s_mov_b32 s39, 0
	v_and_b32_e32 v102, 48, v39
	v_lshlrev_b32_e32 v26, 4, v26
	v_lshlrev_b32_e32 v42, 4, v42
	v_lshlrev_b32_e32 v25, 4, v25
	v_lshlrev_b32_e32 v20, 4, v20
	v_lshlrev_b32_e32 v74, 1, v65
	v_add_lshl_u32 v22, v37, v90, 1
	v_add_lshl_u32 v11, v11, v37, 1
	v_writelane_b32 v255, s97, 32
	v_lshl_or_b32 v129, v38, 4, v9
	s_add_i32 s3, 0, 0x15c00
	s_add_i32 s88, s22, 0
	s_add_i32 s89, s23, 0
	s_add_i32 s90, s24, 0
	v_add_u32_e32 v9, 0, v66
	v_add_u32_e32 v152, 0x12800, v8
	v_mbcnt_lo_u32_b32 v8, -1, 0
	s_mov_b64 s[52:53], s[38:39]
	v_add_u32_e32 v107, s70, v89
	v_lshlrev_b32_e32 v45, 4, v45
	v_cndmask_b32_e64 v65, 0, 1.0, vcc
	v_add_u32_e32 v127, 0x2d00, v103
	v_writelane_b32 v255, s29, 44
	v_or_b32_e32 v130, 0x3500, v102
	v_add_u32_e32 v131, v28, v68
	v_add_u32_e32 v132, v28, v26
	v_add_u32_e32 v133, v29, v42
	v_add_u32_e32 v134, v29, v69
	v_add_u32_e32 v135, s3, v70
	v_add_u32_e32 v136, s3, v71
	s_mov_b32 s86, 0x4038aa3b
	s_add_i32 s67, 0, 0x10000
	v_add_u32_e32 v137, v28, v72
	v_add_u32_e32 v138, v28, v25
	v_add_u32_e32 v139, v29, v75
	v_add_u32_e32 v140, v29, v20
	v_add_u32_e32 v141, s3, v73
	v_add_u32_e32 v142, s3, v74
	v_add_u32_e32 v143, v32, v33
	v_add_u32_e32 v145, v34, v35
	s_mov_b32 s87, 0xbfb8aa3b
	v_add_u32_e32 v146, v36, v44
	s_add_i32 s88, s88, 0x23900
	s_add_i32 s89, s89, 0x23900
	s_add_i32 s90, s90, 0x23900
	s_add_i32 s91, 0, 0x27900
	s_add_i32 s92, s81, 0x400
	s_add_i32 s93, s81, 0x800
	s_add_i32 s94, s81, 0xc00
	s_add_i32 s95, s81, 0x1400
	s_add_i32 s96, s81, 0x1800
	s_add_i32 s97, s81, 0x1c00
	s_add_i32 s3, 0, 0x16100
	s_add_i32 s69, 0, 0x18500
	v_mov_b32_e32 v147, 0xbf92477c
	v_add_u32_e32 v148, v40, v27
	s_xor_b64 s[54:55], s[26:27], -1
	v_add_u32_e32 v149, 0, v43
	v_add_u32_e32 v150, 0x12400, v9
	v_mov_b32_e32 v153, 0x3a27c5ac
	v_mbcnt_hi_u32_b32 v144, -1, v8
	v_add_u32_e32 v154, s71, v22
	v_add_u32_e32 v155, s71, v23
	v_add_u32_e32 v156, s71, v11
	s_mov_b32 s33, s28
	s_mov_b32 s29, 0
	v_add_u32_e32 v228, s67, v116
	v_add_u32_e32 v207, v92, v45
	v_add_u32_e32 v231, s3, v118
	v_add_u32_e32 v216, v94, v112
	v_xor_b32_e32 v242, 16, v144
	v_and_b32_e32 v241, 64, v144
	v_add_u32_e32 v21, 64, v241
	v_cmp_lt_i32_e32 vcc, v242, v21
	s_nop 1
	v_cndmask_b32_e32 v20, v144, v242, vcc
	v_lshlrev_b32_e32 v221, 2, v20
	v_add_u32_e32 v236, s69, v121
	v_add_u32_e32 v210, v96, v108
	v_or_b32_e32 v240, v102, v241
	v_add_u32_e32 v218, v96, v112
	v_add_u32_e32 v219, v93, v111
	v_add_u32_e32 v235, s3, v121
	v_add_u32_e32 v214, s71, v110
	v_xor_b32_e32 v243, 32, v144
	v_add_u32_e32 v239, 0x12600, v97
	v_add_u32_e32 v224, s71, v114
	v_add_u32_e32 v226, s83, v102
	v_add_u32_e32 v215, v92, v111
	v_add_u32_e32 v233, s67, v119
	v_add_u32_e32 v227, s67, v115
	v_cmp_lt_i32_e32 vcc, v243, v21
	s_nop 1
	v_cndmask_b32_e32 v22, v144, v243, vcc
	v_lshlrev_b32_e32 v222, 2, v22
	v_add_u32_e32 v230, s69, v117
	v_add_u32_e32 v212, v91, v45
	v_add_u32_e32 v238, s69, v122
	v_add_u32_e32 v234, s67, v120
	v_add_u32_e32 v209, v95, v108
	v_add_u32_e32 v211, v93, v45
	v_add_u32_e32 v217, v95, v112
	v_add_u32_e32 v232, s69, v118
	v_add_u32_e32 v208, v94, v108
	v_add_u32_e32 v229, s3, v117
	v_add_u32_e32 v225, 0x15d80, v44
	v_add_u32_e32 v213, s67, v109
	v_add_u32_e32 v223, s67, v113
	v_add_u32_e32 v220, v91, v111
	v_add_u32_e32 v237, s3, v122
	s_waitcnt vmcnt(0)

.LBB0_645:
	s_nop 7
	v_or_b32_e32 v130, s54, v143
	v_lshl_or_b32 v131, v142, 11, s55
	s_lshl_b32 s10, s20, 9
	v_readlane_b32 s18, v255, 6
	v_or_b32_e32 v132, v131, v130
	s_or_b32 s10, s21, s10
	v_readlane_b32 s19, v255, 7
	v_add_u32_e32 v128, s10, v132
	v_readlane_b32 s14, v255, 2
	v_readlane_b32 s15, v255, 3
	s_mov_b64 s[14:15], s[18:19]
	global_load_dwordx4 v[156:159], v128, s[24:25]
	s_nop 2
	global_load_dwordx4 v[160:163], v128, s[14:15]
	v_or_b32_e32 v133, 0x100, v128
	global_load_dwordx4 v[168:171], v128, s[14:15] offset:256
	global_load_dwordx4 v[164:167], v133, s[24:25]
	v_add_u32_e32 v248, 0x8000, v128
	v_add_u32_e32 v132, 0x8100, v128
	global_load_dwordx4 v[172:175], v248, s[24:25]
	global_load_dwordx4 v[176:179], v248, s[14:15]
	global_load_dwordx4 v[180:183], v132, s[24:25]
	global_load_dwordx4 v[184:187], v248, s[14:15] offset:256
	v_mov_b32_e32 v249, v129
	v_lshl_add_u64 v[212:213], s[22:23], 0, v[128:129]
	v_lshl_add_u64 v[216:217], s[22:23], 0, v[248:249]
	v_lshl_add_u64 v[214:215], v[212:213], 0, s[8:9]
	v_lshl_add_u64 v[218:219], v[216:217], 0, s[8:9]
	v_readlane_b32 s16, v255, 4
	v_readlane_b32 s17, v255, 5
	v_readlane_b32 s12, v255, 0
	v_readlane_b32 s13, v255, 1
	s_mov_b64 s[12:13], s[16:17]
	s_waitcnt vmcnt(7)
	v_cvt_f32_f16_e32 v134, v157
	v_cvt_f32_f16_sdwa v135, v157 dst_sel:DWORD dst_unused:UNUSED_PAD src0_sel:WORD_1
	v_cvt_f32_f16_e32 v138, v156
	v_cvt_f32_f16_sdwa v139, v156 dst_sel:DWORD dst_unused:UNUSED_PAD src0_sel:WORD_1
	v_cvt_f32_f16_e32 v148, v158
	v_cvt_f32_f16_sdwa v149, v158 dst_sel:DWORD dst_unused:UNUSED_PAD src0_sel:WORD_1
	s_waitcnt vmcnt(6)
	v_cvt_f32_f16_e32 v150, v161
	v_cvt_f32_f16_sdwa v151, v161 dst_sel:DWORD dst_unused:UNUSED_PAD src0_sel:WORD_1
	v_cvt_f32_f16_e32 v154, v160
	v_cvt_f32_f16_sdwa v155, v160 dst_sel:DWORD dst_unused:UNUSED_PAD src0_sel:WORD_1
	v_cvt_f32_f16_e32 v246, v162
	v_cvt_f32_f16_sdwa v247, v162 dst_sel:DWORD dst_unused:UNUSED_PAD src0_sel:WORD_1
	v_pk_fma_f32 v[124:125], v[124:125], v[154:155], v[138:139]
	v_pk_fma_f32 v[126:127], v[126:127], v[150:151], v[134:135]
	v_pk_fma_f32 v[120:121], v[120:121], v[246:247], v[148:149]
	s_waitcnt vmcnt(4)
	v_cvt_f32_f16_e32 v252, v164
	v_cvt_f32_f16_sdwa v253, v164 dst_sel:DWORD dst_unused:UNUSED_PAD src0_sel:WORD_1
	v_cvt_f32_f16_e32 v138, v167
	v_cvt_f32_f16_sdwa v139, v167 dst_sel:DWORD dst_unused:UNUSED_PAD src0_sel:WORD_1
	v_cvt_f32_f16_e32 v154, v166
	v_cvt_f32_f16_sdwa v155, v166 dst_sel:DWORD dst_unused:UNUSED_PAD src0_sel:WORD_1
	v_cvt_f32_f16_e32 v150, v168
	v_cvt_f32_f16_sdwa v151, v168 dst_sel:DWORD dst_unused:UNUSED_PAD src0_sel:WORD_1
	v_cvt_f32_f16_e32 v148, v171
	v_cvt_f32_f16_e32 v246, v170
	v_cvt_f32_f16_sdwa v247, v170 dst_sel:DWORD dst_unused:UNUSED_PAD src0_sel:WORD_1
	v_cvt_f32_f16_sdwa v149, v171 dst_sel:DWORD dst_unused:UNUSED_PAD src0_sel:WORD_1
	v_pk_fma_f32 v[116:117], v[116:117], v[150:151], v[252:253]
	v_pk_fma_f32 v[112:113], v[112:113], v[246:247], v[154:155]
	v_pk_fma_f32 v[114:115], v[114:115], v[148:149], v[138:139]
	s_waitcnt vmcnt(3)
	v_cvt_f32_f16_e32 v150, v175
	v_cvt_f32_f16_sdwa v151, v175 dst_sel:DWORD dst_unused:UNUSED_PAD src0_sel:WORD_1
	s_waitcnt vmcnt(2)
	v_cvt_f32_f16_e32 v154, v179
	v_cvt_f32_f16_sdwa v155, v179 dst_sel:DWORD dst_unused:UNUSED_PAD src0_sel:WORD_1
	v_add_u32_e32 v138, 0x10000, v128
	v_pk_fma_f32 v[106:107], v[106:107], v[154:155], v[150:151]
	global_load_dwordx4 v[188:191], v138, s[24:25]
	global_load_dwordx4 v[192:195], v138, s[14:15]
	v_add_u32_e32 v154, 0x10100, v128
	global_load_dwordx4 v[200:203], v138, s[14:15] offset:256
	global_load_dwordx4 v[196:199], v154, s[24:25]
	v_cvt_f32_f16_e32 v144, v159
	v_cvt_f32_f16_sdwa v145, v159 dst_sel:DWORD dst_unused:UNUSED_PAD src0_sel:WORD_1
	v_cvt_f32_f16_e32 v244, v163
	v_cvt_f32_f16_sdwa v245, v163 dst_sel:DWORD dst_unused:UNUSED_PAD src0_sel:WORD_1
	v_cvt_f32_f16_e32 v250, v165
	v_cvt_f32_f16_sdwa v251, v165 dst_sel:DWORD dst_unused:UNUSED_PAD src0_sel:WORD_1
	v_cvt_f32_f16_e32 v134, v169
	v_cvt_f32_f16_sdwa v135, v169 dst_sel:DWORD dst_unused:UNUSED_PAD src0_sel:WORD_1
	v_pk_fma_f32 v[122:123], v[122:123], v[244:245], v[144:145]
	v_pk_fma_f32 v[118:119], v[118:119], v[134:135], v[250:251]
	v_cvt_f32_f16_e32 v144, v173
	v_cvt_f32_f16_sdwa v145, v173 dst_sel:DWORD dst_unused:UNUSED_PAD src0_sel:WORD_1
	v_cvt_f32_f16_e32 v244, v172
	v_cvt_f32_f16_sdwa v245, v172 dst_sel:DWORD dst_unused:UNUSED_PAD src0_sel:WORD_1
	v_cvt_f32_f16_e32 v252, v174
	v_cvt_f32_f16_sdwa v253, v174 dst_sel:DWORD dst_unused:UNUSED_PAD src0_sel:WORD_1
	v_cvt_f32_f16_e32 v134, v177
	v_cvt_f32_f16_sdwa v135, v177 dst_sel:DWORD dst_unused:UNUSED_PAD src0_sel:WORD_1
	v_cvt_f32_f16_e32 v250, v176
	v_cvt_f32_f16_sdwa v251, v176 dst_sel:DWORD dst_unused:UNUSED_PAD src0_sel:WORD_1
	v_cvt_f32_f16_e32 v246, v178
	v_cvt_f32_f16_sdwa v247, v178 dst_sel:DWORD dst_unused:UNUSED_PAD src0_sel:WORD_1
	v_pk_fma_f32 v[108:109], v[108:109], v[250:251], v[244:245]
	v_pk_fma_f32 v[110:111], v[110:111], v[134:135], v[144:145]
	v_pk_fma_f32 v[104:105], v[104:105], v[246:247], v[252:253]
	s_waitcnt vmcnt(5)
	v_cvt_f32_f16_e32 v148, v181
	v_cvt_f32_f16_sdwa v149, v181 dst_sel:DWORD dst_unused:UNUSED_PAD src0_sel:WORD_1
	v_cvt_f32_f16_e32 v244, v180
	v_cvt_f32_f16_sdwa v245, v180 dst_sel:DWORD dst_unused:UNUSED_PAD src0_sel:WORD_1
	v_cvt_f32_f16_e32 v134, v182
	v_cvt_f32_f16_sdwa v135, v182 dst_sel:DWORD dst_unused:UNUSED_PAD src0_sel:WORD_1
	s_waitcnt vmcnt(4)
	v_cvt_f32_f16_e32 v144, v185
	v_cvt_f32_f16_sdwa v145, v185 dst_sel:DWORD dst_unused:UNUSED_PAD src0_sel:WORD_1
	v_cvt_f32_f16_e32 v246, v184
	v_cvt_f32_f16_sdwa v247, v184 dst_sel:DWORD dst_unused:UNUSED_PAD src0_sel:WORD_1
	v_cvt_f32_f16_e32 v150, v186
	v_cvt_f32_f16_sdwa v151, v186 dst_sel:DWORD dst_unused:UNUSED_PAD src0_sel:WORD_1
	v_pk_fma_f32 v[100:101], v[100:101], v[246:247], v[244:245]
	v_pk_fma_f32 v[102:103], v[102:103], v[144:145], v[148:149]
	v_pk_fma_f32 v[96:97], v[96:97], v[150:151], v[134:135]
	v_cvt_f32_f16_e32 v250, v183
	v_cvt_f32_f16_sdwa v251, v183 dst_sel:DWORD dst_unused:UNUSED_PAD src0_sel:WORD_1
	v_cvt_f32_f16_e32 v252, v187
	v_cvt_f32_f16_sdwa v253, v187 dst_sel:DWORD dst_unused:UNUSED_PAD src0_sel:WORD_1
	v_mov_b32_e32 v139, v129
	v_pk_fma_f32 v[98:99], v[98:99], v[252:253], v[250:251]
	v_add_u32_e32 v250, 0x18000, v128
	v_lshl_add_u64 v[220:221], s[22:23], 0, v[138:139]
	global_load_dwordx4 v[204:207], v250, s[24:25]
	global_load_dwordx4 v[208:211], v250, s[14:15]
	global_load_dwordx4 v[160:163], v250, s[14:15] offset:256
	v_mov_b32_e32 v251, v129
	v_cvt_pk_f16_f32 v123, v122, v123
	v_lshl_add_u64 v[224:225], s[22:23], 0, v[250:251]
	v_cvt_pk_f16_f32 v122, v120, v121
	v_cvt_pk_f16_f32 v115, v114, v115
	v_cvt_pk_f16_f32 v121, v126, v127
	v_cvt_pk_f16_f32 v120, v124, v125
	v_cvt_pk_f16_f32 v114, v112, v113
	v_cvt_pk_f16_f32 v107, v106, v107
	v_cvt_pk_f16_f32 v113, v118, v119
	v_cvt_pk_f16_f32 v112, v116, v117
	v_cvt_pk_f16_f32 v106, v104, v105
	v_cvt_pk_f16_f32 v99, v98, v99
	v_cvt_pk_f16_f32 v105, v110, v111
	v_cvt_pk_f16_f32 v104, v108, v109
	v_cvt_pk_f16_f32 v98, v96, v97
	v_cvt_pk_f16_f32 v97, v102, v103
	v_cvt_pk_f16_f32 v96, v100, v101
	v_lshl_add_u64 v[222:223], v[220:221], 0, s[8:9]
	v_lshl_add_u64 v[226:227], v[224:225], 0, s[8:9]
	s_waitcnt vmcnt(6)
	v_cvt_f32_f16_e32 v248, v188
	v_cvt_f32_f16_sdwa v249, v188 dst_sel:DWORD dst_unused:UNUSED_PAD src0_sel:WORD_1
	v_cvt_f32_f16_e32 v246, v190
	v_cvt_f32_f16_sdwa v247, v190 dst_sel:DWORD dst_unused:UNUSED_PAD src0_sel:WORD_1
	s_waitcnt vmcnt(5)
	v_cvt_f32_f16_e32 v148, v192
	v_cvt_f32_f16_sdwa v149, v192 dst_sel:DWORD dst_unused:UNUSED_PAD src0_sel:WORD_1
	v_cvt_f32_f16_e32 v150, v194
	v_cvt_f32_f16_sdwa v151, v194 dst_sel:DWORD dst_unused:UNUSED_PAD src0_sel:WORD_1
	v_pk_fma_f32 v[92:93], v[92:93], v[148:149], v[248:249]
	v_pk_fma_f32 v[88:89], v[88:89], v[150:151], v[246:247]
	s_waitcnt vmcnt(3)
	v_cvt_f32_f16_e32 v248, v199
	v_cvt_f32_f16_sdwa v249, v199 dst_sel:DWORD dst_unused:UNUSED_PAD src0_sel:WORD_1
	v_cvt_f32_f16_e32 v246, v203
	v_cvt_f32_f16_sdwa v247, v203 dst_sel:DWORD dst_unused:UNUSED_PAD src0_sel:WORD_1
	v_cvt_f32_f16_e32 v244, v191
	v_cvt_f32_f16_sdwa v245, v191 dst_sel:DWORD dst_unused:UNUSED_PAD src0_sel:WORD_1
	v_cvt_f32_f16_e32 v134, v195
	v_cvt_f32_f16_sdwa v135, v195 dst_sel:DWORD dst_unused:UNUSED_PAD src0_sel:WORD_1
	v_pk_fma_f32 v[82:83], v[82:83], v[246:247], v[248:249]
	v_or_b32_e32 v246, s10, v130
	v_pk_fma_f32 v[90:91], v[90:91], v[134:135], v[244:245]
	v_add_u32_e32 v244, 0x18100, v128
	v_add_u32_e32 v248, v131, v246
	global_load_dwordx4 v[156:159], v244, s[24:25]
	v_add_u32_e32 v128, 0x40000, v248
	v_add_u32_e32 v245, 0x40100, v248
	global_load_dwordx4 v[164:167], v128, s[24:25]
	global_load_dwordx4 v[168:171], v128, s[14:15]
	v_lshl_add_u64 v[228:229], s[22:23], 0, v[128:129]
	global_load_dwordx4 v[172:175], v245, s[24:25]
	global_load_dwordx4 v[176:179], v128, s[14:15] offset:256
	v_add_u32_e32 v128, 0x48000, v248
	v_add_u32_e32 v244, 0x48100, v248
	global_load_dwordx4 v[180:183], v128, s[24:25]
	global_load_dwordx4 v[184:187], v128, s[14:15]
	v_cvt_f32_f16_e32 v132, v189
	v_cvt_f32_f16_sdwa v133, v189 dst_sel:DWORD dst_unused:UNUSED_PAD src0_sel:WORD_1
	v_cvt_f32_f16_e32 v144, v193
	v_cvt_f32_f16_sdwa v145, v193 dst_sel:DWORD dst_unused:UNUSED_PAD src0_sel:WORD_1
	v_lshl_add_u64 v[232:233], s[22:23], 0, v[128:129]
	global_load_dwordx4 v[188:191], v244, s[24:25]
	global_load_dwordx4 v[192:195], v128, s[14:15] offset:256
	v_add_u32_e32 v128, 0x50000, v248
	v_pk_fma_f32 v[94:95], v[94:95], v[144:145], v[132:133]
	v_cvt_f32_f16_e32 v252, v197
	v_cvt_f32_f16_sdwa v253, v197 dst_sel:DWORD dst_unused:UNUSED_PAD src0_sel:WORD_1
	v_cvt_f32_f16_e32 v148, v196
	v_cvt_f32_f16_sdwa v149, v196 dst_sel:DWORD dst_unused:UNUSED_PAD src0_sel:WORD_1
	v_cvt_f32_f16_e32 v132, v198
	v_cvt_f32_f16_sdwa v133, v198 dst_sel:DWORD dst_unused:UNUSED_PAD src0_sel:WORD_1
	v_cvt_f32_f16_e32 v144, v201
	v_cvt_f32_f16_sdwa v145, v201 dst_sel:DWORD dst_unused:UNUSED_PAD src0_sel:WORD_1
	v_cvt_f32_f16_e32 v150, v200
	v_cvt_f32_f16_sdwa v151, v200 dst_sel:DWORD dst_unused:UNUSED_PAD src0_sel:WORD_1
	v_cvt_f32_f16_e32 v134, v202
	v_cvt_f32_f16_sdwa v135, v202 dst_sel:DWORD dst_unused:UNUSED_PAD src0_sel:WORD_1
	global_load_dwordx4 v[196:199], v128, s[24:25]
	global_load_dwordx4 v[200:203], v128, s[14:15]
	v_pk_fma_f32 v[84:85], v[84:85], v[150:151], v[148:149]
	v_pk_fma_f32 v[86:87], v[86:87], v[144:145], v[252:253]
	v_pk_fma_f32 v[80:81], v[80:81], v[134:135], v[132:133]
	s_waitcnt vmcnt(13)
	v_cvt_f32_f16_e32 v154, v205
	v_cvt_f32_f16_sdwa v155, v205 dst_sel:DWORD dst_unused:UNUSED_PAD src0_sel:WORD_1
	v_cvt_f32_f16_e32 v138, v204
	v_cvt_f32_f16_sdwa v139, v204 dst_sel:DWORD dst_unused:UNUSED_PAD src0_sel:WORD_1
	v_cvt_f32_f16_e32 v148, v207
	v_cvt_f32_f16_sdwa v149, v207 dst_sel:DWORD dst_unused:UNUSED_PAD src0_sel:WORD_1
	v_cvt_f32_f16_e32 v150, v206
	v_cvt_f32_f16_sdwa v151, v206 dst_sel:DWORD dst_unused:UNUSED_PAD src0_sel:WORD_1
	s_waitcnt vmcnt(12)
	v_cvt_f32_f16_e32 v144, v209
	v_cvt_f32_f16_sdwa v145, v209 dst_sel:DWORD dst_unused:UNUSED_PAD src0_sel:WORD_1
	v_cvt_f32_f16_e32 v252, v208
	v_cvt_f32_f16_sdwa v253, v208 dst_sel:DWORD dst_unused:UNUSED_PAD src0_sel:WORD_1
	v_cvt_f32_f16_e32 v132, v211
	v_cvt_f32_f16_e32 v134, v210
	v_cvt_f32_f16_sdwa v135, v210 dst_sel:DWORD dst_unused:UNUSED_PAD src0_sel:WORD_1
	v_cvt_f32_f16_sdwa v133, v211 dst_sel:DWORD dst_unused:UNUSED_PAD src0_sel:WORD_1
	v_pk_fma_f32 v[76:77], v[76:77], v[252:253], v[138:139]
	v_pk_fma_f32 v[78:79], v[78:79], v[144:145], v[154:155]
	v_pk_fma_f32 v[72:73], v[72:73], v[134:135], v[150:151]
	v_pk_fma_f32 v[74:75], v[74:75], v[132:133], v[148:149]
	s_waitcnt vmcnt(11)
	v_cvt_f32_f16_e32 v134, v161
	v_cvt_f32_f16_sdwa v135, v161 dst_sel:DWORD dst_unused:UNUSED_PAD src0_sel:WORD_1
	v_cvt_f32_f16_e32 v150, v160
	v_cvt_f32_f16_sdwa v151, v160 dst_sel:DWORD dst_unused:UNUSED_PAD src0_sel:WORD_1
	v_cvt_f32_f16_e32 v148, v162
	v_cvt_f32_f16_sdwa v149, v162 dst_sel:DWORD dst_unused:UNUSED_PAD src0_sel:WORD_1
	v_cvt_f32_f16_e32 v132, v163
	v_cvt_f32_f16_sdwa v133, v163 dst_sel:DWORD dst_unused:UNUSED_PAD src0_sel:WORD_1
	v_lshl_add_u64 v[236:237], s[22:23], 0, v[128:129]
	global_load_dwordx4 v[208:211], v128, s[14:15] offset:256
	v_add_u32_e32 v128, 0x58000, v248
	v_cvt_pk_f16_f32 v91, v90, v91
	global_load_dwordx4 v[160:163], v128, s[14:15]
	v_cvt_pk_f16_f32 v90, v88, v89
	v_cvt_pk_f16_f32 v83, v82, v83
	v_cvt_pk_f16_f32 v89, v94, v95
	v_cvt_pk_f16_f32 v88, v92, v93
	v_cvt_pk_f16_f32 v82, v80, v81
	v_cvt_pk_f16_f32 v75, v74, v75
	v_cvt_pk_f16_f32 v81, v86, v87
	v_cvt_pk_f16_f32 v80, v84, v85
	v_cvt_pk_f16_f32 v74, v72, v73
	v_cvt_pk_f16_f32 v73, v78, v79
	v_cvt_pk_f16_f32 v72, v76, v77
	v_lshl_add_u64 v[240:241], s[22:23], 0, v[128:129]
	v_lshl_add_u64 v[230:231], v[228:229], 0, s[8:9]
	v_lshl_add_u64 v[234:235], v[232:233], 0, s[8:9]
	v_lshl_add_u64 v[238:239], v[236:237], 0, s[8:9]
	v_lshl_add_u64 v[242:243], v[240:241], 0, s[8:9]
	s_waitcnt vmcnt(12)
	v_cvt_f32_f16_e32 v138, v157
	v_cvt_f32_f16_sdwa v139, v157 dst_sel:DWORD dst_unused:UNUSED_PAD src0_sel:WORD_1
	v_cvt_f32_f16_e32 v252, v156
	v_cvt_f32_f16_sdwa v253, v156 dst_sel:DWORD dst_unused:UNUSED_PAD src0_sel:WORD_1
	v_cvt_f32_f16_e32 v154, v158
	v_cvt_f32_f16_sdwa v155, v158 dst_sel:DWORD dst_unused:UNUSED_PAD src0_sel:WORD_1
	v_pk_fma_f32 v[68:69], v[68:69], v[150:151], v[252:253]
	v_pk_fma_f32 v[70:71], v[70:71], v[134:135], v[138:139]
	v_pk_fma_f32 v[64:65], v[64:65], v[148:149], v[154:155]
	v_cvt_f32_f16_e32 v144, v159
	v_cvt_f32_f16_sdwa v145, v159 dst_sel:DWORD dst_unused:UNUSED_PAD src0_sel:WORD_1
	s_waitcnt vmcnt(11)
	v_cvt_f32_f16_e32 v250, v165
	v_cvt_f32_f16_sdwa v251, v165 dst_sel:DWORD dst_unused:UNUSED_PAD src0_sel:WORD_1
	v_cvt_f32_f16_e32 v130, v164
	v_cvt_f32_f16_sdwa v131, v164 dst_sel:DWORD dst_unused:UNUSED_PAD src0_sel:WORD_1
	v_cvt_f32_f16_e32 v150, v166
	v_cvt_f32_f16_sdwa v151, v166 dst_sel:DWORD dst_unused:UNUSED_PAD src0_sel:WORD_1
	s_waitcnt vmcnt(10)
	v_cvt_f32_f16_e32 v252, v169
	v_cvt_f32_f16_sdwa v253, v169 dst_sel:DWORD dst_unused:UNUSED_PAD src0_sel:WORD_1
	v_cvt_f32_f16_e32 v134, v168
	v_cvt_f32_f16_sdwa v135, v168 dst_sel:DWORD dst_unused:UNUSED_PAD src0_sel:WORD_1
	v_cvt_f32_f16_e32 v148, v170
	v_cvt_f32_f16_sdwa v149, v170 dst_sel:DWORD dst_unused:UNUSED_PAD src0_sel:WORD_1
	v_pk_fma_f32 v[66:67], v[66:67], v[132:133], v[144:145]
	v_pk_fma_f32 v[60:61], v[60:61], v[134:135], v[130:131]
	v_pk_fma_f32 v[62:63], v[62:63], v[252:253], v[250:251]
	v_pk_fma_f32 v[56:57], v[56:57], v[148:149], v[150:151]
	v_cvt_f32_f16_e32 v246, v167
	v_cvt_f32_f16_sdwa v247, v167 dst_sel:DWORD dst_unused:UNUSED_PAD src0_sel:WORD_1
	v_cvt_f32_f16_e32 v138, v171
	v_cvt_f32_f16_sdwa v139, v171 dst_sel:DWORD dst_unused:UNUSED_PAD src0_sel:WORD_1
	s_waitcnt vmcnt(9)
	v_cvt_f32_f16_e32 v154, v173
	v_cvt_f32_f16_sdwa v155, v173 dst_sel:DWORD dst_unused:UNUSED_PAD src0_sel:WORD_1
	v_cvt_f32_f16_e32 v132, v172
	v_cvt_f32_f16_sdwa v133, v172 dst_sel:DWORD dst_unused:UNUSED_PAD src0_sel:WORD_1
	v_cvt_f32_f16_e32 v130, v174
	v_cvt_f32_f16_sdwa v131, v174 dst_sel:DWORD dst_unused:UNUSED_PAD src0_sel:WORD_1
	s_waitcnt vmcnt(8)
	v_cvt_f32_f16_e32 v134, v177
	v_cvt_f32_f16_sdwa v135, v177 dst_sel:DWORD dst_unused:UNUSED_PAD src0_sel:WORD_1
	v_cvt_f32_f16_e32 v250, v176
	v_cvt_f32_f16_sdwa v251, v176 dst_sel:DWORD dst_unused:UNUSED_PAD src0_sel:WORD_1
	v_cvt_f32_f16_e32 v148, v178
	v_cvt_f32_f16_sdwa v149, v178 dst_sel:DWORD dst_unused:UNUSED_PAD src0_sel:WORD_1
	v_pk_fma_f32 v[58:59], v[58:59], v[138:139], v[246:247]
	v_pk_fma_f32 v[52:53], v[52:53], v[250:251], v[132:133]
	v_pk_fma_f32 v[54:55], v[54:55], v[134:135], v[154:155]
	v_pk_fma_f32 v[48:49], v[48:49], v[148:149], v[130:131]
	v_cvt_f32_f16_e32 v144, v175
	v_cvt_f32_f16_sdwa v145, v175 dst_sel:DWORD dst_unused:UNUSED_PAD src0_sel:WORD_1
	v_cvt_f32_f16_e32 v252, v179
	v_cvt_f32_f16_sdwa v253, v179 dst_sel:DWORD dst_unused:UNUSED_PAD src0_sel:WORD_1
	s_waitcnt vmcnt(7)
	v_cvt_f32_f16_e32 v150, v181
	v_cvt_f32_f16_sdwa v151, v181 dst_sel:DWORD dst_unused:UNUSED_PAD src0_sel:WORD_1
	v_cvt_f32_f16_e32 v138, v180
	v_cvt_f32_f16_sdwa v139, v180 dst_sel:DWORD dst_unused:UNUSED_PAD src0_sel:WORD_1
	v_cvt_f32_f16_e32 v132, v182
	v_cvt_f32_f16_sdwa v133, v182 dst_sel:DWORD dst_unused:UNUSED_PAD src0_sel:WORD_1
	s_waitcnt vmcnt(6)
	v_cvt_f32_f16_e32 v250, v185
	v_cvt_f32_f16_sdwa v251, v185 dst_sel:DWORD dst_unused:UNUSED_PAD src0_sel:WORD_1
	v_cvt_f32_f16_e32 v134, v184
	v_cvt_f32_f16_sdwa v135, v184 dst_sel:DWORD dst_unused:UNUSED_PAD src0_sel:WORD_1
	v_cvt_f32_f16_e32 v130, v186
	v_cvt_f32_f16_sdwa v131, v186 dst_sel:DWORD dst_unused:UNUSED_PAD src0_sel:WORD_1
	v_pk_fma_f32 v[50:51], v[50:51], v[252:253], v[144:145]
	v_pk_fma_f32 v[44:45], v[44:45], v[134:135], v[138:139]
	v_pk_fma_f32 v[46:47], v[46:47], v[250:251], v[150:151]
	v_pk_fma_f32 v[40:41], v[40:41], v[130:131], v[132:133]
	s_waitcnt vmcnt(5)
	v_cvt_f32_f16_e32 v144, v188
	v_cvt_f32_f16_sdwa v145, v188 dst_sel:DWORD dst_unused:UNUSED_PAD src0_sel:WORD_1
	v_cvt_f32_f16_e32 v134, v190
	v_cvt_f32_f16_sdwa v135, v190 dst_sel:DWORD dst_unused:UNUSED_PAD src0_sel:WORD_1
	s_waitcnt vmcnt(4)
	v_cvt_f32_f16_e32 v150, v192
	v_cvt_f32_f16_sdwa v151, v192 dst_sel:DWORD dst_unused:UNUSED_PAD src0_sel:WORD_1
	v_cvt_f32_f16_e32 v130, v194
	v_cvt_f32_f16_sdwa v131, v194 dst_sel:DWORD dst_unused:UNUSED_PAD src0_sel:WORD_1
	v_add_u32_e32 v132, 0x50100, v248
	v_pk_fma_f32 v[36:37], v[36:37], v[150:151], v[144:145]
	v_pk_fma_f32 v[32:33], v[32:33], v[130:131], v[134:135]
	global_load_dwordx4 v[204:207], v132, s[24:25]
	s_waitcnt vmcnt(4)
	v_cvt_f32_f16_e32 v144, v198
	v_cvt_f32_f16_sdwa v145, v198 dst_sel:DWORD dst_unused:UNUSED_PAD src0_sel:WORD_1
	s_waitcnt vmcnt(3)
	v_cvt_f32_f16_e32 v130, v202
	v_cvt_f32_f16_sdwa v131, v202 dst_sel:DWORD dst_unused:UNUSED_PAD src0_sel:WORD_1
	global_load_dwordx4 v[156:159], v128, s[24:25]
	v_pk_fma_f32 v[24:25], v[24:25], v[130:131], v[144:145]
	v_add_u32_e32 v144, 0x58100, v248
	global_load_dwordx4 v[168:171], v128, s[14:15] offset:256
	global_load_dwordx4 v[164:167], v144, s[24:25]
	v_cvt_f32_f16_e32 v246, v183
	v_cvt_f32_f16_sdwa v247, v183 dst_sel:DWORD dst_unused:UNUSED_PAD src0_sel:WORD_1
	v_cvt_f32_f16_e32 v154, v187
	v_cvt_f32_f16_sdwa v155, v187 dst_sel:DWORD dst_unused:UNUSED_PAD src0_sel:WORD_1
	v_cvt_f32_f16_e32 v148, v189
	v_cvt_f32_f16_sdwa v149, v189 dst_sel:DWORD dst_unused:UNUSED_PAD src0_sel:WORD_1
	v_cvt_f32_f16_e32 v138, v193
	v_cvt_f32_f16_sdwa v139, v193 dst_sel:DWORD dst_unused:UNUSED_PAD src0_sel:WORD_1
	v_pk_fma_f32 v[42:43], v[42:43], v[154:155], v[246:247]
	v_cvt_f32_f16_e32 v252, v191
	v_cvt_f32_f16_sdwa v253, v191 dst_sel:DWORD dst_unused:UNUSED_PAD src0_sel:WORD_1
	v_cvt_f32_f16_e32 v250, v195
	v_cvt_f32_f16_sdwa v251, v195 dst_sel:DWORD dst_unused:UNUSED_PAD src0_sel:WORD_1
	v_cvt_f32_f16_e32 v154, v197
	v_cvt_f32_f16_sdwa v155, v197 dst_sel:DWORD dst_unused:UNUSED_PAD src0_sel:WORD_1
	v_cvt_f32_f16_e32 v150, v201
	v_cvt_f32_f16_sdwa v151, v201 dst_sel:DWORD dst_unused:UNUSED_PAD src0_sel:WORD_1
	v_pk_fma_f32 v[38:39], v[38:39], v[138:139], v[148:149]
	v_cvt_f32_f16_e32 v246, v196
	v_cvt_f32_f16_sdwa v247, v196 dst_sel:DWORD dst_unused:UNUSED_PAD src0_sel:WORD_1
	v_cvt_f32_f16_e32 v138, v200
	v_cvt_f32_f16_sdwa v139, v200 dst_sel:DWORD dst_unused:UNUSED_PAD src0_sel:WORD_1
	v_pk_fma_f32 v[34:35], v[34:35], v[250:251], v[252:253]
	v_pk_fma_f32 v[30:31], v[30:31], v[150:151], v[154:155]
	v_cvt_f32_f16_e32 v244, v199
	v_cvt_f32_f16_sdwa v245, v199 dst_sel:DWORD dst_unused:UNUSED_PAD src0_sel:WORD_1
	v_cvt_f32_f16_e32 v148, v203
	v_cvt_f32_f16_sdwa v149, v203 dst_sel:DWORD dst_unused:UNUSED_PAD src0_sel:WORD_1
	s_waitcnt vmcnt(5)
	v_cvt_f32_f16_e32 v150, v208
	v_cvt_f32_f16_sdwa v151, v208 dst_sel:DWORD dst_unused:UNUSED_PAD src0_sel:WORD_1
	v_pk_fma_f32 v[28:29], v[28:29], v[138:139], v[246:247]
	v_cvt_f32_f16_e32 v246, v209
	v_cvt_f32_f16_sdwa v247, v209 dst_sel:DWORD dst_unused:UNUSED_PAD src0_sel:WORD_1
	v_pk_fma_f32 v[26:27], v[26:27], v[148:149], v[244:245]
	v_cvt_f32_f16_e32 v154, v211
	v_cvt_f32_f16_e32 v130, v210
	v_cvt_f32_f16_sdwa v131, v210 dst_sel:DWORD dst_unused:UNUSED_PAD src0_sel:WORD_1
	v_cvt_f32_f16_sdwa v155, v211 dst_sel:DWORD dst_unused:UNUSED_PAD src0_sel:WORD_1
	v_cvt_pk_f16_f32 v67, v66, v67
	v_cvt_pk_f16_f32 v66, v64, v65
	v_cvt_pk_f16_f32 v59, v58, v59
	v_cvt_pk_f16_f32 v65, v70, v71
	v_cvt_pk_f16_f32 v64, v68, v69
	v_cvt_pk_f16_f32 v58, v56, v57
	v_cvt_pk_f16_f32 v51, v50, v51
	global_store_dwordx4 v[212:213], v[120:123], off sc1
	s_nop 1
	v_cvt_pk_f16_f32 v57, v62, v63
	v_cvt_pk_f16_f32 v56, v60, v61
	v_cvt_pk_f16_f32 v50, v48, v49
	v_cvt_pk_f16_f32 v43, v42, v43
	global_store_dwordx4 v[214:215], v[112:115], off sc1
	s_nop 1
	v_cvt_pk_f16_f32 v49, v54, v55
	v_cvt_pk_f16_f32 v48, v52, v53
	v_cvt_pk_f16_f32 v42, v40, v41
	v_cvt_pk_f16_f32 v35, v34, v35
	global_store_dwordx4 v[216:217], v[104:107], off sc1
	s_nop 1
	v_cvt_pk_f16_f32 v41, v46, v47
	v_cvt_pk_f16_f32 v40, v44, v45
	v_cvt_pk_f16_f32 v34, v32, v33
	v_cvt_pk_f16_f32 v27, v26, v27
	global_store_dwordx4 v[218:219], v[96:99], off sc1
	s_nop 1
	v_cvt_pk_f16_f32 v33, v38, v39
	v_cvt_pk_f16_f32 v32, v36, v37
	v_cvt_pk_f16_f32 v26, v24, v25
	global_store_dwordx4 v[220:221], v[88:91], off sc1
	s_nop 1
	v_cvt_pk_f16_f32 v25, v30, v31
	v_cvt_pk_f16_f32 v24, v28, v29
	global_store_dwordx4 v[222:223], v[80:83], off sc1
	s_nop 1
	global_store_dwordx4 v[224:225], v[72:75], off sc1
	s_nop 1
	global_store_dwordx4 v[226:227], v[64:67], off sc1
	s_nop 1
	global_store_dwordx4 v[228:229], v[56:59], off sc1
	s_nop 1
	global_store_dwordx4 v[230:231], v[48:51], off sc1
	s_nop 1
	global_store_dwordx4 v[232:233], v[40:43], off sc1
	s_nop 1
	global_store_dwordx4 v[234:235], v[32:35], off sc1
	s_nop 1
	global_store_dwordx4 v[236:237], v[24:27], off sc1
	s_nop 1
	s_waitcnt vmcnt(16)
	v_cvt_f32_f16_e32 v250, v204
	v_cvt_f32_f16_sdwa v251, v204 dst_sel:DWORD dst_unused:UNUSED_PAD src0_sel:WORD_1
	v_cvt_f32_f16_e32 v134, v205
	v_cvt_f32_f16_sdwa v135, v205 dst_sel:DWORD dst_unused:UNUSED_PAD src0_sel:WORD_1
	v_pk_fma_f32 v[20:21], v[20:21], v[150:151], v[250:251]
	v_cvt_f32_f16_e32 v252, v207
	v_cvt_f32_f16_sdwa v253, v207 dst_sel:DWORD dst_unused:UNUSED_PAD src0_sel:WORD_1
	v_cvt_f32_f16_e32 v138, v206
	v_cvt_f32_f16_sdwa v139, v206 dst_sel:DWORD dst_unused:UNUSED_PAD src0_sel:WORD_1
	s_waitcnt vmcnt(15)
	v_cvt_f32_f16_e32 v148, v157
	v_cvt_f32_f16_sdwa v149, v157 dst_sel:DWORD dst_unused:UNUSED_PAD src0_sel:WORD_1
	v_cvt_f32_f16_e32 v250, v161
	v_cvt_f32_f16_sdwa v251, v161 dst_sel:DWORD dst_unused:UNUSED_PAD src0_sel:WORD_1
	v_pk_fma_f32 v[22:23], v[22:23], v[246:247], v[134:135]
	v_cvt_f32_f16_e32 v244, v156
	v_cvt_f32_f16_sdwa v245, v156 dst_sel:DWORD dst_unused:UNUSED_PAD src0_sel:WORD_1
	v_cvt_f32_f16_e32 v134, v160
	v_cvt_f32_f16_sdwa v135, v160 dst_sel:DWORD dst_unused:UNUSED_PAD src0_sel:WORD_1
	v_pk_fma_f32 v[16:17], v[16:17], v[130:131], v[138:139]
	v_pk_fma_f32 v[18:19], v[18:19], v[154:155], v[252:253]
	v_cvt_f32_f16_e32 v132, v159
	v_cvt_f32_f16_sdwa v133, v159 dst_sel:DWORD dst_unused:UNUSED_PAD src0_sel:WORD_1
	v_cvt_f32_f16_e32 v246, v163
	v_cvt_f32_f16_sdwa v247, v163 dst_sel:DWORD dst_unused:UNUSED_PAD src0_sel:WORD_1
	v_pk_fma_f32 v[14:15], v[14:15], v[250:251], v[148:149]
	v_cvt_f32_f16_e32 v150, v158
	v_cvt_f32_f16_sdwa v151, v158 dst_sel:DWORD dst_unused:UNUSED_PAD src0_sel:WORD_1
	v_cvt_f32_f16_e32 v130, v162
	v_cvt_f32_f16_sdwa v131, v162 dst_sel:DWORD dst_unused:UNUSED_PAD src0_sel:WORD_1
	s_waitcnt vmcnt(13)
	v_cvt_f32_f16_e32 v252, v167
	v_cvt_f32_f16_sdwa v253, v167 dst_sel:DWORD dst_unused:UNUSED_PAD src0_sel:WORD_1
	v_cvt_f32_f16_e32 v148, v171
	v_cvt_f32_f16_sdwa v149, v171 dst_sel:DWORD dst_unused:UNUSED_PAD src0_sel:WORD_1
	v_pk_fma_f32 v[12:13], v[12:13], v[134:135], v[244:245]
	v_cvt_f32_f16_e32 v248, v166
	v_cvt_f32_f16_sdwa v249, v166 dst_sel:DWORD dst_unused:UNUSED_PAD src0_sel:WORD_1
	v_cvt_f32_f16_e32 v250, v170
	v_cvt_f32_f16_sdwa v251, v170 dst_sel:DWORD dst_unused:UNUSED_PAD src0_sel:WORD_1
	v_cvt_f32_f16_e32 v138, v165
	v_cvt_f32_f16_sdwa v139, v165 dst_sel:DWORD dst_unused:UNUSED_PAD src0_sel:WORD_1
	v_cvt_f32_f16_e32 v154, v164
	v_cvt_f32_f16_sdwa v155, v164 dst_sel:DWORD dst_unused:UNUSED_PAD src0_sel:WORD_1
	v_cvt_f32_f16_e32 v134, v169
	v_cvt_f32_f16_sdwa v135, v169 dst_sel:DWORD dst_unused:UNUSED_PAD src0_sel:WORD_1
	v_cvt_f32_f16_e32 v244, v168
	v_cvt_f32_f16_sdwa v245, v168 dst_sel:DWORD dst_unused:UNUSED_PAD src0_sel:WORD_1
	v_pk_fma_f32 v[10:11], v[10:11], v[246:247], v[132:133]
	v_pk_fma_f32 v[8:9], v[8:9], v[130:131], v[150:151]
	v_pk_fma_f32 v[2:3], v[2:3], v[148:149], v[252:253]
	v_pk_fma_f32 v[0:1], v[0:1], v[250:251], v[248:249]
	v_pk_fma_f32 v[4:5], v[4:5], v[244:245], v[154:155]
	v_pk_fma_f32 v[6:7], v[6:7], v[134:135], v[138:139]
	v_cvt_pk_f16_f32 v19, v18, v19
	v_cvt_pk_f16_f32 v18, v16, v17
	v_cvt_pk_f16_f32 v11, v10, v11
	v_cvt_pk_f16_f32 v17, v22, v23
	v_cvt_pk_f16_f32 v16, v20, v21
	v_cvt_pk_f16_f32 v10, v8, v9
	v_cvt_pk_f16_f32 v3, v2, v3
	v_cvt_pk_f16_f32 v9, v14, v15
	v_cvt_pk_f16_f32 v8, v12, v13
	v_cvt_pk_f16_f32 v2, v0, v1
	v_cvt_pk_f16_f32 v1, v6, v7
	v_cvt_pk_f16_f32 v0, v4, v5
	global_store_dwordx4 v[238:239], v[16:19], off sc1
	s_nop 1
	global_store_dwordx4 v[240:241], v[8:11], off sc1
	s_nop 1
	global_store_dwordx4 v[242:243], v[0:3], off sc1
	s_nop 1
	s_waitcnt vmcnt(0)
	s_barrier
	v_mbcnt_lo_u32_b32 v0, -1, 0
	v_mbcnt_hi_u32_b32 v0, -1, v0
	s_nop 0
	v_or_b32_e32 v0, s97, v0
	v_cmp_eq_u32_e32 vcc, 0, v0
	s_and_saveexec_b64 s[10:11], vcc
	s_cbranch_execz .LBB0_596
	s_mov_b64 s[14:15], exec
	v_mbcnt_lo_u32_b32 v0, s14, 0
	v_mbcnt_hi_u32_b32 v0, s15, v0
	v_cmp_eq_u32_e32 vcc, 0, v0
	s_and_saveexec_b64 s[12:13], vcc
	s_cbranch_execz .LBB0_648
	s_lshl_b32 s0, s0, 6
	s_lshl_b64 s[16:17], s[0:1], 2
	s_add_u32 s16, s56, s16
	s_addc_u32 s17, s57, s17
	s_bcnt1_i32_b64 s0, s[14:15]
	v_mov_b32_e32 v0, s0
	global_atomic_add v129, v0, s[16:17]
